# PRE load-burst removal: + V-row loads moved behind the b1/b2 stage barriers with zero-page masking (on top of spread lora-fragment and next-item prefetch loads)
# baseline (speedup 1.0000x reference)
.LBB0_109:
	s_or_b64 exec, exec, s[38:39]
	v_mov_b32_e32 v2, v180
	v_mov_b32_e32 v20, s76
	s_waitcnt lgkmcnt(0)
	v_and_b32_e32 v3, 31, v2
	v_ashrrev_i32_e32 v2, 5, v2
	v_or_b32_e32 v90, s43, v3
	v_or_b32_e32 v3, s91, v3
	v_mad_u32_u24 v91, v90, s64, v20
	v_lshlrev_b32_e32 v20, 4, v2
	v_mul_u32_u24_e32 v3, 0x90, v3
	v_mov_b32_e32 v53, 0
	v_add_u32_e32 v21, v91, v20
	v_add3_u32 v3, s76, v3, v20
	ds_read_b128 v[36:39], v21
	ds_read_b128 v[54:57], v21 offset:32
	ds_read_b128 v[58:61], v21 offset:64
	ds_read_b128 v[62:65], v21 offset:96
	ds_read_b128 v[20:23], v3 offset:18432
	ds_read_b128 v[66:69], v3 offset:18464
	ds_read_b128 v[70:73], v3 offset:18496
	ds_read_b128 v[74:77], v3 offset:18528
	ds_read_b128 v[40:43], v3 offset:27648
	ds_read_b128 v[78:81], v3 offset:27680
	ds_read_b128 v[82:85], v3 offset:27712
	ds_read_b128 v[86:89], v3 offset:27744
	v_mov_b32_e32 v52, 0
	s_waitcnt lgkmcnt(7)
	v_mfma_f32_32x32x16_bf16 v[20:35], v[20:23], v[36:39], 0
	v_lshl_add_u32 v3, v2, 2, s91
	v_cmp_lt_i32_e32 vcc, v3, v90
	v_lshlrev_b32_e32 v2, 3, v2
	v_readlane_b32 s38, v252, 16
	s_waitcnt lgkmcnt(3)
	v_mfma_f32_32x32x16_bf16 v[36:51], v[40:43], v[36:39], 0
	v_mfma_f32_32x32x16_bf16 v[20:35], v[66:69], v[54:57], v[20:35]
	s_waitcnt lgkmcnt(2)
	v_mfma_f32_32x32x16_bf16 v[36:51], v[78:81], v[54:57], v[36:51]
	v_or_b32_e32 v54, 1, v3
	v_mfma_f32_32x32x16_bf16 v[20:35], v[70:73], v[58:61], v[20:35]
	v_mov_b32_e32 v72, 0
	v_mov_b32_e32 v73, 0
	s_waitcnt lgkmcnt(1)
	v_mfma_f32_32x32x16_bf16 v[36:51], v[82:85], v[58:61], v[36:51]
	v_mfma_f32_32x32x16_bf16 v[20:35], v[74:77], v[62:65], v[20:35]
	v_mov_b32_e32 v74, 0
	v_mov_b32_e32 v75, 0
	s_waitcnt lgkmcnt(0)
	v_mfma_f32_32x32x16_bf16 v[36:51], v[86:89], v[62:65], v[36:51]
	s_nop 7
	v_cndmask_b32_e64 v20, 0, -v20, vcc
	s_nop 2
	v_cndmask_b32_e32 v36, 0, v36, vcc
	v_cmp_lt_i32_e32 vcc, v54, v90
	v_or_b32_e32 v54, 2, v3
	s_nop 0
	v_cndmask_b32_e64 v21, 0, -v21, vcc
	v_cndmask_b32_e32 v37, 0, v37, vcc
	v_cmp_lt_i32_e32 vcc, v54, v90
	v_or_b32_e32 v54, 3, v3
	s_nop 0
	v_cndmask_b32_e64 v22, 0, -v22, vcc
	v_cndmask_b32_e32 v38, 0, v38, vcc
	v_cmp_lt_i32_e32 vcc, v54, v90
	v_add_u32_e32 v54, 8, v3
	s_nop 0
	v_cndmask_b32_e64 v23, 0, -v23, vcc
	v_cndmask_b32_e32 v39, 0, v39, vcc
	v_cmp_lt_i32_e32 vcc, v54, v90
	v_add_u32_e32 v54, 9, v3
	s_nop 0
	v_cndmask_b32_e64 v24, 0, -v24, vcc
	v_cndmask_b32_e32 v40, 0, v40, vcc
	v_cmp_lt_i32_e32 vcc, v54, v90
	v_add_u32_e32 v54, 10, v3
	s_nop 0
	v_cndmask_b32_e64 v25, 0, -v25, vcc
	v_cndmask_b32_e32 v41, 0, v41, vcc
	v_cmp_lt_i32_e32 vcc, v54, v90
	v_add_u32_e32 v54, 11, v3
	s_nop 0
	v_cndmask_b32_e64 v26, 0, -v26, vcc
	v_cndmask_b32_e32 v42, 0, v42, vcc
	v_cmp_lt_i32_e32 vcc, v54, v90
	v_add_u32_e32 v54, 16, v3
	s_nop 0
	v_cndmask_b32_e64 v27, 0, -v27, vcc
	v_cndmask_b32_e32 v43, 0, v43, vcc
	v_cmp_lt_i32_e32 vcc, v54, v90
	v_add_u32_e32 v54, 17, v3
	s_nop 0
	v_cndmask_b32_e64 v28, 0, -v28, vcc
	v_cndmask_b32_e32 v44, 0, v44, vcc
	v_cmp_lt_i32_e32 vcc, v54, v90
	v_add_u32_e32 v54, 18, v3
	s_nop 0
	v_cndmask_b32_e64 v29, 0, -v29, vcc
	v_cndmask_b32_e32 v45, 0, v45, vcc
	v_cmp_lt_i32_e32 vcc, v54, v90
	v_add_u32_e32 v54, 19, v3
	s_nop 0
	v_cndmask_b32_e64 v30, 0, -v30, vcc
	v_cndmask_b32_e32 v46, 0, v46, vcc
	v_cmp_lt_i32_e32 vcc, v54, v90
	v_add_u32_e32 v54, 24, v3
	s_nop 0
	v_cndmask_b32_e64 v31, 0, -v31, vcc
	v_cndmask_b32_e32 v47, 0, v47, vcc
	v_cmp_lt_i32_e32 vcc, v54, v90
	v_add_u32_e32 v54, 25, v3
	s_nop 0
	v_cndmask_b32_e64 v32, 0, -v32, vcc
	v_cndmask_b32_e32 v48, 0, v48, vcc
	v_cmp_lt_i32_e32 vcc, v54, v90
	v_add_u32_e32 v54, 26, v3
	v_add_u32_e32 v3, 27, v3
	v_cndmask_b32_e64 v33, 0, -v33, vcc
	v_cndmask_b32_e32 v49, 0, v49, vcc
	v_cmp_lt_i32_e32 vcc, v54, v90
	v_add3_u32 v54, v91, v2, s28
	v_cvt_pk_bf16_f32 v2, v20, v21
	v_cndmask_b32_e64 v34, 0, -v34, vcc
	v_cndmask_b32_e32 v50, 0, v50, vcc
	v_cmp_lt_i32_e32 vcc, v3, v90
	v_cvt_pk_bf16_f32 v3, v22, v23
	v_cvt_pk_bf16_f32 v20, v24, v25
	v_cndmask_b32_e64 v35, 0, -v35, vcc
	v_cvt_pk_bf16_f32 v21, v26, v27
	v_add_u32_e32 v22, 0x9000, v54
	ds_write2_b64 v22, v[2:3], v[20:21] offset1:2
	v_cvt_pk_bf16_f32 v2, v28, v29
	v_cvt_pk_bf16_f32 v3, v30, v31
	v_cvt_pk_bf16_f32 v20, v32, v33
	v_cvt_pk_bf16_f32 v21, v34, v35
	ds_write2_b64 v22, v[2:3], v[20:21] offset0:4 offset1:6
	v_cvt_pk_bf16_f32 v2, v53, v53
	v_mov_b32_e32 v3, v2
	v_add_u32_e32 v20, 0xb000, v54
	v_cndmask_b32_e32 v51, 0, v51, vcc
	ds_write2_b64 v20, v[2:3], v[2:3] offset0:128 offset1:130
	ds_write2_b64 v20, v[2:3], v[2:3] offset0:132 offset1:134
	v_cvt_pk_bf16_f32 v2, v36, v37
	v_cvt_pk_bf16_f32 v3, v38, v39
	v_cvt_pk_bf16_f32 v20, v40, v41
	v_cvt_pk_bf16_f32 v21, v42, v43
	v_add_u32_e32 v22, 0xd800, v54
	ds_write2_b64 v22, v[2:3], v[20:21] offset1:2
	v_cvt_pk_bf16_f32 v2, v44, v45
	v_cvt_pk_bf16_f32 v3, v46, v47
	v_cvt_pk_bf16_f32 v20, v48, v49
	v_cvt_pk_bf16_f32 v21, v50, v51
	ds_write2_b64 v22, v[2:3], v[20:21] offset0:4 offset1:6
	v_mov_b32_e32 v2, v180
	s_waitcnt lgkmcnt(0)
	s_barrier
	v_readlane_b32 s101, v252, 16
	v_add_u32_e32 v250, s42, v180
	v_lshrrev_b32_e32 v251, 2, v250
	v_bfe_u32 v250, v250, 2, 6
	v_bitop3_b32 v251, v251, 63, v251 bitop3:0xc
	v_cndmask_b32_e64 v250, v251, v250, s[36:37]
	v_or_b32_e32 v250, s56, v250
	s_lshl_b32 s100, s68, 12
	v_or_b32_e32 v251, s100, v250
	v_lshlrev_b32_e32 v241, 10, v251
	v_lshlrev_b32_e32 v251, 4, v180
	v_and_b32_e32 v242, 48, v251
	v_or_b32_e32 v242, s101, v242
	v_lshl_add_u32 v241, v242, 1, v241
	v_add_u32_e32 v241, 0x6c00000, v241
	v_add_u32_e32 v242, 0xfffffc00, v241
	v_add_u32_e32 v243, 0x400, v241
	v_cmp_ne_u32_e32 vcc, 0, v250
	s_movk_i32 s100, 0xfff
	s_nop 0
	v_cndmask_b32_e32 v242, v251, v242, vcc
	v_cmp_ne_u32_e32 vcc, s100, v250
	s_nop 1
	v_cndmask_b32_e32 v243, v251, v243, vcc
	s_mov_b64 s[38:39], -1
	s_and_b64 vcc, exec, s[78:79]
	s_cbranch_vccz .LBB0_119
	v_mov_b32_e32 v1, v180
	s_nop 0
	v_and_b32_e32 v2, 31, v1
	v_ashrrev_i32_e32 v1, 5, v1
	v_or_b32_e32 v3, s91, v2
	v_or_b32_e32 v2, s43, v2
	v_mul_u32_u24_e32 v3, 0x90, v3
	v_lshlrev_b32_e32 v24, 4, v1
	v_mul_u32_u24_e32 v25, 0x90, v2
	v_add3_u32 v3, s76, v3, v24
	v_add3_u32 v24, s76, v25, v24
	ds_read_b128 v[20:23], v3 offset:18432
	ds_read_b128 v[76:79], v3 offset:18464
	ds_read_b128 v[80:83], v3 offset:18496
	ds_read_b128 v[84:87], v3 offset:18528
	ds_read_b128 v[36:39], v24 offset:9216
	ds_read_b128 v[88:91], v24 offset:9248
	ds_read_b128 v[92:95], v24 offset:9280
	ds_read_b128 v[96:99], v24 offset:9312
	ds_read_b128 v[40:43], v3 offset:27648
	ds_read_b128 v[182:185], v3 offset:27680
	ds_read_b128 v[186:189], v3 offset:27712
	ds_read_b128 v[190:193], v3 offset:27744
	s_waitcnt lgkmcnt(7)
	v_mfma_f32_32x32x16_bf16 v[20:35], v[20:23], v[36:39], 0
	v_lshl_add_u32 v3, v1, 2, s91
	v_cmp_gt_i32_e32 vcc, v3, v2
	v_lshlrev_b32_e32 v1, 3, v1
	s_waitcnt lgkmcnt(3)
	v_mfma_f32_32x32x16_bf16 v[36:51], v[40:43], v[36:39], 0
	v_mfma_f32_32x32x16_bf16 v[20:35], v[76:79], v[88:91], v[20:35]
	s_waitcnt lgkmcnt(2)
	v_mfma_f32_32x32x16_bf16 v[36:51], v[182:185], v[88:91], v[36:51]
	v_mfma_f32_32x32x16_bf16 v[20:35], v[80:83], v[92:95], v[20:35]
	s_waitcnt lgkmcnt(1)
	v_mfma_f32_32x32x16_bf16 v[36:51], v[186:189], v[92:95], v[36:51]
	v_mfma_f32_32x32x16_bf16 v[20:35], v[84:87], v[96:99], v[20:35]
	s_waitcnt lgkmcnt(0)
	v_mfma_f32_32x32x16_bf16 v[36:51], v[190:193], v[96:99], v[36:51]
	s_nop 9
	v_cndmask_b32_e64 v76, v20, 0, vcc
	s_nop 0
	v_cndmask_b32_e64 v20, v36, 0, vcc
	v_cmp_lt_i32_e32 vcc, v3, v2
	s_nop 1
	v_cndmask_b32_e32 v36, 0, v21, vcc
	v_cndmask_b32_e32 v21, 0, v37, vcc
	v_or_b32_e32 v37, 2, v3
	v_cmp_gt_i32_e32 vcc, v37, v2
	s_nop 1
	v_cndmask_b32_e64 v37, v22, 0, vcc
	v_cndmask_b32_e64 v22, v38, 0, vcc
	v_or_b32_e32 v38, 3, v3
	v_cmp_gt_i32_e32 vcc, v38, v2
	s_nop 1
	v_cndmask_b32_e64 v38, v23, 0, vcc
	v_cndmask_b32_e64 v23, v39, 0, vcc
	v_add_u32_e32 v39, 8, v3
	v_cmp_gt_i32_e32 vcc, v39, v2
	s_nop 1
	v_cndmask_b32_e64 v39, v24, 0, vcc
	v_cndmask_b32_e64 v24, v40, 0, vcc
	v_add_u32_e32 v40, 9, v3
	v_cmp_gt_i32_e32 vcc, v40, v2
	s_nop 1
	v_cndmask_b32_e64 v40, v25, 0, vcc
	v_cndmask_b32_e64 v25, v41, 0, vcc
	v_add_u32_e32 v41, 10, v3
	v_cmp_gt_i32_e32 vcc, v41, v2
	s_nop 1
	v_cndmask_b32_e64 v41, v26, 0, vcc
	v_cndmask_b32_e64 v26, v42, 0, vcc
	v_add_u32_e32 v42, 11, v3
	v_cmp_gt_i32_e32 vcc, v42, v2
	s_nop 1
	v_cndmask_b32_e64 v42, v27, 0, vcc
	v_cndmask_b32_e64 v27, v43, 0, vcc
	v_add_u32_e32 v43, 16, v3
	v_cmp_gt_i32_e32 vcc, v43, v2
	s_nop 1
	v_cndmask_b32_e64 v43, v28, 0, vcc
	v_cndmask_b32_e64 v28, v44, 0, vcc
	v_add_u32_e32 v44, 17, v3
	v_cmp_gt_i32_e32 vcc, v44, v2
	s_nop 1
	v_cndmask_b32_e64 v44, v29, 0, vcc
	v_cndmask_b32_e64 v29, v45, 0, vcc
	v_add_u32_e32 v45, 18, v3
	v_cmp_gt_i32_e32 vcc, v45, v2
	s_nop 1
	v_cndmask_b32_e64 v45, v30, 0, vcc
	v_cndmask_b32_e64 v30, v46, 0, vcc
	v_add_u32_e32 v46, 19, v3
	v_cmp_gt_i32_e32 vcc, v46, v2
	s_nop 1
	v_cndmask_b32_e64 v46, v31, 0, vcc
	v_cndmask_b32_e64 v31, v47, 0, vcc
	v_add_u32_e32 v47, 24, v3
	v_cmp_gt_i32_e32 vcc, v47, v2
	s_nop 1
	v_cndmask_b32_e64 v47, v32, 0, vcc
	v_cndmask_b32_e64 v32, v48, 0, vcc
	v_add_u32_e32 v48, 25, v3
	v_cmp_gt_i32_e32 vcc, v48, v2
	s_nop 1
	v_cndmask_b32_e64 v48, v33, 0, vcc
	v_cndmask_b32_e64 v33, v49, 0, vcc
	v_add_u32_e32 v49, 26, v3
	v_cmp_gt_i32_e32 vcc, v49, v2
	v_add_u32_e32 v3, 27, v3
	s_nop 0
	v_cndmask_b32_e64 v49, v34, 0, vcc
	v_cndmask_b32_e64 v34, v50, 0, vcc
	v_cmp_gt_i32_e32 vcc, v3, v2
	v_mov_b32_e32 v3, s29
	v_mad_u32_u24 v2, v2, s64, v3
	v_cndmask_b32_e64 v50, v35, 0, vcc
	v_add3_u32 v1, v2, v1, s28
	v_cvt_pk_bf16_f32 v2, v76, v36
	v_cvt_pk_bf16_f32 v3, v37, v38
	v_cvt_pk_bf16_f32 v36, v39, v40
	v_cvt_pk_bf16_f32 v37, v41, v42
	v_cndmask_b32_e64 v35, v51, 0, vcc
	ds_write2_b64 v1, v[2:3], v[36:37] offset1:2
	v_cvt_pk_bf16_f32 v2, v43, v44
	v_cvt_pk_bf16_f32 v3, v45, v46
	v_cvt_pk_bf16_f32 v36, v47, v48
	v_cvt_pk_bf16_f32 v37, v49, v50
	ds_write2_b64 v1, v[2:3], v[36:37] offset0:4 offset1:6
	v_mov_b64_e32 v[50:51], v[34:35]
	v_mov_b64_e32 v[48:49], v[32:33]
	v_mov_b64_e32 v[46:47], v[30:31]
	v_mov_b64_e32 v[44:45], v[28:29]
	v_mov_b64_e32 v[42:43], v[26:27]
	v_mov_b64_e32 v[40:41], v[24:25]
	v_mov_b64_e32 v[38:39], v[22:23]
	v_mov_b64_e32 v[36:37], v[20:21]
	s_cbranch_execz .LBB0_120
	s_branch .LBB0_121

.LBB0_121:
	s_waitcnt lgkmcnt(0)
	s_barrier
	global_load_dwordx4 v[68:71], v241, s[98:99]
	global_load_dwordx4 v[56:59], v241, s[98:99] offset:16
	global_load_dwordx4 v[72:75], v242, s[98:99]
	v_cndmask_b32_e64 v2, 0, 1, s[80:81]
	v_mov_b32_e32 v1, v180
	v_cmp_ne_u32_e64 s[38:39], 1, v2
	s_andn2_b64 vcc, exec, s[80:81]
	s_cbranch_vccnz .LBB0_123
	v_and_b32_e32 v18, 31, v1
	v_ashrrev_i32_e32 v19, 5, v1
	v_or_b32_e32 v2, s43, v18
	v_mul_u32_u24_e32 v2, 0x90, v2
	v_lshlrev_b32_e32 v3, 4, v19
	v_lshrrev_b32_e32 v4, 2, v1
	v_add3_u32 v2, s0, v2, v3
	v_and_b32_e32 v3, 16, v1
	v_and_b32_e32 v5, 0xffffff8, v4
	v_lshlrev_b32_e32 v1, 2, v1
	v_add_u32_e32 v5, s43, v5
	v_and_b32_e32 v1, 12, v1
	v_and_or_b32 v4, v4, 3, v5
	v_or3_b32 v1, v3, v1, s43
	v_mul_lo_u32 v4, v4, s64
	v_lshlrev_b32_e32 v1, 1, v1
	v_add3_u32 v1, s76, v4, v1
	ds_read_b128 v[2:5], v2 offset:36864
	ds_read_b64_tr_b16 v[6:7], v1 offset:46080
	ds_read_b64_tr_b16 v[8:9], v1 offset:46656
	v_cmp_lt_u32_e32 vcc, 15, v18
	v_mul_u32_u24_e32 v1, 0x90, v18
	v_lshlrev_b32_e32 v18, 3, v19
	s_waitcnt lgkmcnt(2)
	v_cndmask_b32_e32 v5, 0, v5, vcc
	v_cndmask_b32_e32 v4, 0, v4, vcc
	v_cndmask_b32_e32 v3, 0, v3, vcc
	v_cndmask_b32_e32 v2, 0, v2, vcc
	v_add3_u32 v1, s1, v1, v18
	s_waitcnt lgkmcnt(0)
	v_mfma_f32_32x32x16_bf16 v[2:17], v[6:9], v[2:5], 0
	s_nop 11
	v_cvt_pk_bf16_f32 v2, v2, v3
	v_cvt_pk_bf16_f32 v3, v4, v5
	v_cvt_pk_bf16_f32 v4, v6, v7
	v_cvt_pk_bf16_f32 v5, v8, v9
	ds_write2_b64 v1, v[2:3], v[4:5] offset0:8 offset1:10
	v_cvt_pk_bf16_f32 v2, v10, v11
	v_cvt_pk_bf16_f32 v3, v12, v13
	v_cvt_pk_bf16_f32 v4, v14, v15
	v_cvt_pk_bf16_f32 v5, v16, v17
	ds_write2_b64 v1, v[2:3], v[4:5] offset0:12 offset1:14
.LBB0_123:
	s_waitcnt lgkmcnt(0)
	s_barrier
	global_load_dwordx4 v[60:63], v242, s[98:99] offset:16
	global_load_dwordx4 v[52:55], v243, s[98:99]
	global_load_dwordx4 v[64:67], v243, s[98:99] offset:16
	v_mov_b32_e32 v1, v180
	s_and_b64 vcc, exec, s[38:39]
	s_cbranch_vccnz .LBB0_125
	v_and_or_b32 v2, v1, 31, s43
	v_mov_b32_e32 v3, s0
	v_ashrrev_i32_e32 v18, 5, v1
	v_mad_u32_u24 v19, v2, s64, v3
	v_and_b32_e32 v12, 16, v1
	v_lshrrev_b32_e32 v13, 2, v1
	v_lshlrev_b32_e32 v1, 2, v1
	v_lshl_add_u32 v2, v18, 3, v19
	v_and_b32_e32 v13, 0xffffffb, v13
	v_and_or_b32 v1, v1, 12, v12
	v_add_u32_e32 v84, 0xb000, v2
	v_lshlrev_b32_e32 v1, 1, v1
	v_mul_lo_u32 v12, v13, s64
	ds_read2_b64 v[6:9], v84 offset0:128 offset1:130
	ds_read2_b64 v[14:17], v84 offset0:132 offset1:134
	v_add3_u32 v1, s1, v1, v12
	v_lshl_add_u32 v18, v18, 4, v19
	ds_read_b64_tr_b16 v[76:77], v1 offset:64
	ds_read_b64_tr_b16 v[78:79], v1 offset:640
	ds_read_b128 v[80:83], v18 offset:46080
	s_waitcnt lgkmcnt(4)
	v_lshlrev_b32_e32 v2, 16, v6
	v_and_b32_e32 v3, 0xffff0000, v6
	v_lshlrev_b32_e32 v4, 16, v7
	v_and_b32_e32 v5, 0xffff0000, v7
	v_lshlrev_b32_e32 v6, 16, v8
	v_and_b32_e32 v7, 0xffff0000, v8
	v_lshlrev_b32_e32 v8, 16, v9
	v_and_b32_e32 v9, 0xffff0000, v9
	s_waitcnt lgkmcnt(3)
	v_lshlrev_b32_e32 v10, 16, v14
	v_and_b32_e32 v11, 0xffff0000, v14
	v_lshlrev_b32_e32 v12, 16, v15
	v_and_b32_e32 v13, 0xffff0000, v15
	v_lshlrev_b32_e32 v14, 16, v16
	v_and_b32_e32 v15, 0xffff0000, v16
	v_lshlrev_b32_e32 v16, 16, v17
	v_and_b32_e32 v17, 0xffff0000, v17
	s_waitcnt lgkmcnt(0)
	s_nop 0
	v_mfma_f32_32x32x16_bf16 v[2:17], v[76:79], v[80:83], v[2:17]
	ds_read_b64_tr_b16 v[76:77], v1 offset:2368
	ds_read_b64_tr_b16 v[78:79], v1 offset:2944
	ds_read_b128 v[80:83], v18 offset:46112
	s_waitcnt lgkmcnt(0)
	v_mfma_f32_32x32x16_bf16 v[2:17], v[76:79], v[80:83], v[2:17]
	s_nop 11
	v_cvt_pk_bf16_f32 v2, v2, v3
	v_cvt_pk_bf16_f32 v3, v4, v5
	v_cvt_pk_bf16_f32 v4, v6, v7
	v_cvt_pk_bf16_f32 v5, v8, v9
	ds_write2_b64 v84, v[2:3], v[4:5] offset0:128 offset1:130
	v_cvt_pk_bf16_f32 v2, v10, v11
	v_cvt_pk_bf16_f32 v3, v12, v13
	v_cvt_pk_bf16_f32 v4, v14, v15
	v_cvt_pk_bf16_f32 v5, v16, v17
	ds_write2_b64 v84, v[2:3], v[4:5] offset0:132 offset1:134
